# v47 + widened partial-O epilogue stores + static s_setprio 1 for waves 4-7 in the attention loop
# baseline (speedup 1.0000x reference)
; #define GAS __attribute__((address_space(1)))
; DI float xr16_sum(float x) { float a = x, b = x; XR_SWAP("v_permlane16_swap_b32", a, b); return a + b; }
; DI float xr32_sum(float x) { float a = x, b = x; XR_SWAP("v_permlane32_swap_b32", a, b); return a + b; }
; DI u32x2 pk4_(const f32x4 v) { u32x2 o; o.x = pk2(v.x, v.y); o.y = pk2(v.z, v.w); return o; }
; DI void u_attn2(Frame& F, int h, int qb, int sp, int ntile) {
;     ...
;                 ps = xr32_sum(xr16_sum(ps));
;     ...
;     const int slot = att_slot(h, qb, sp);
;     bf16* po = (bf16*)(ws + WS_APO) + (size_t)slot * 32768; float* pm = (float*)(ws + WS_APM) + (size_t)slot * 512;
; #pragma unroll
;     for (int db = 0; db < 8; ++db)
; #pragma unroll
;         for (int qq = 0; qq < 2; ++qq) *(GAS u32x2*)(po + (size_t)(w * 32 + qq * 16 + lc) * 128 + db * 16 + 4 * g4) = pk4_(o[db][qq]);
;     if (g4 == 0) {
; #pragma unroll
;         for (int qq = 0; qq < 2; ++qq) { *(GAS f32x2*)(pm + (w * 32 + qq * 16 + lc) * 2) = (f32x2){mrun[qq], lrun[qq]}; } }
.LBB0_2245:
	s_or_b64 exec, exec, s[30:31]
	v_mov_b32_e32 v18, v165
	v_mov_b32_e32 v20, v163
	s_nop 0
	v_permlane16_swap_b32 v165, v18
	v_permlane16_swap_b32 v163, v20
	s_nop 0
	v_add_f32_e32 v165, v165, v18
	v_add_f32_e32 v163, v163, v20
	v_mov_b32_e32 v18, v165
	v_mov_b32_e32 v20, v163
	s_nop 0
	v_permlane32_swap_b32 v165, v18
	v_permlane32_swap_b32 v163, v20
	s_nop 0
	v_add_f32_e32 v165, v165, v18
	v_add_f32_e32 v163, v163, v20
	v_lshrrev_b32_e32 v2, 2, v177
	v_add_u32_e32 v4, 1, v2
	v_lshlrev_b32_e32 v2, 1, v2
	v_sub_u32_e32 v2, v177, v2
	v_mul_u32_u24_e32 v3, 0x90, v178
	v_mul_i32_i24_e32 v2, v2, v4
	v_add3_u32 v2, v176, v3, v2
	v_ashrrev_i32_e32 v3, 31, v2
	v_lshlrev_b64 v[4:5], 16, v[2:3]
	v_lshl_add_u64 v[8:9], s[22:23], 0, v[4:5]
	v_or_b32_e32 v4, s42, v161
	v_mov_b32_e32 v161, v19
	v_lshrrev_b32_e32 v6, 3, v160
	v_and_b32_e32 v7, 1, v6
	v_lshrrev_b32_e32 v6, 1, v6
	v_lshlrev_b32_e32 v6, 4, v6
	v_lshl_or_b32 v6, v7, 5, v6
	v_mov_b32_e32 v7, v19
	v_ashrrev_i32_e32 v5, 31, v4
	v_or_b32_e32 v14, 16, v4
	v_lshl_add_u64 v[8:9], v[8:9], 0, v[6:7]
	v_lshlrev_b64 v[12:13], 8, v[4:5]
	v_ashrrev_i32_e32 v15, 31, v14
	v_lshl_add_u64 v[12:13], v[8:9], 0, v[12:13]
	v_lshlrev_b64 v[14:15], 8, v[14:15]
	v_lshl_add_u64 v[8:9], v[8:9], 0, v[14:15]
	v_cvt_pk_bf16_f32 v22, v134, v135
	v_cvt_pk_bf16_f32 v23, v136, v137
	v_cvt_pk_bf16_f32 v24, v106, v107
	v_cvt_pk_bf16_f32 v25, v108, v109
	v_cvt_pk_bf16_f32 v26, v118, v119
	v_cvt_pk_bf16_f32 v27, v120, v121
	v_cvt_pk_bf16_f32 v28, v102, v103
	v_cvt_pk_bf16_f32 v29, v104, v105
	v_cvt_pk_bf16_f32 v30, v98, v99
	v_cvt_pk_bf16_f32 v31, v100, v101
	v_cvt_pk_bf16_f32 v32, v90, v91
	v_cvt_pk_bf16_f32 v33, v92, v93
	v_cvt_pk_bf16_f32 v34, v94, v95
	v_cvt_pk_bf16_f32 v35, v96, v97
	v_cvt_pk_bf16_f32 v36, v86, v87
	v_cvt_pk_bf16_f32 v37, v88, v89
	v_cvt_pk_bf16_f32 v38, v82, v83
	v_cvt_pk_bf16_f32 v39, v84, v85
	v_cvt_pk_bf16_f32 v40, v70, v71
	v_cvt_pk_bf16_f32 v41, v72, v73
	v_cvt_pk_bf16_f32 v42, v78, v79
	v_cvt_pk_bf16_f32 v43, v80, v81
	v_cvt_pk_bf16_f32 v44, v74, v75
	v_cvt_pk_bf16_f32 v45, v76, v77
	v_cvt_pk_bf16_f32 v46, v66, v67
	v_cvt_pk_bf16_f32 v47, v68, v69
	v_cvt_pk_bf16_f32 v48, v54, v55
	v_cvt_pk_bf16_f32 v49, v56, v57
	v_cvt_pk_bf16_f32 v50, v58, v59
	v_cvt_pk_bf16_f32 v51, v60, v61
	v_cvt_pk_bf16_f32 v52, v62, v63
	v_cvt_pk_bf16_f32 v53, v64, v65
	s_nop 1
	v_permlane16_swap_b32 v22, v24
	v_permlane16_swap_b32 v23, v25
	v_permlane16_swap_b32 v26, v28
	v_permlane16_swap_b32 v27, v29
	v_permlane16_swap_b32 v30, v32
	v_permlane16_swap_b32 v31, v33
	v_permlane16_swap_b32 v34, v36
	v_permlane16_swap_b32 v35, v37
	v_permlane16_swap_b32 v38, v40
	v_permlane16_swap_b32 v39, v41
	v_permlane16_swap_b32 v42, v44
	v_permlane16_swap_b32 v43, v45
	v_permlane16_swap_b32 v46, v48
	v_permlane16_swap_b32 v47, v49
	v_permlane16_swap_b32 v50, v52
	v_permlane16_swap_b32 v51, v53
	s_nop 0
	global_store_dwordx4 v[12:13], v[22:25], off
	global_store_dwordx4 v[8:9], v[26:29], off
	global_store_dwordx4 v[12:13], v[30:33], off offset:64
	global_store_dwordx4 v[8:9], v[34:37], off offset:64
	global_store_dwordx4 v[12:13], v[38:41], off offset:128
	global_store_dwordx4 v[8:9], v[42:45], off offset:128
	global_store_dwordx4 v[12:13], v[46:49], off offset:192
	global_store_dwordx4 v[8:9], v[50:53], off offset:192
	v_and_b32_e32 v6, 63, v158
	v_cmp_gt_u32_e32 vcc, 16, v6
	s_and_saveexec_b64 s[30:31], vcc
	v_readlane_b32 s46, v235, 30
	v_readlane_b32 s47, v235, 31
	s_cbranch_execz .LBB0_2230
	v_lshlrev_b64 v[2:3], 11, v[2:3]
	v_lshlrev_b32_e32 v4, 1, v4
	v_lshl_add_u64 v[2:3], s[26:27], 0, v[2:3]
	v_ashrrev_i32_e32 v5, 31, v4
	v_lshl_add_u64 v[2:3], v[4:5], 2, v[2:3]
	global_store_dwordx2 v[2:3], v[164:165], off
	global_store_dwordx2 v[2:3], v[162:163], off offset:128
	s_branch .LBB0_2230
